# P2 pn slot-to-tile permutation so each XCD gets same mix of epilogue types, on top of v68 stack
# baseline (speedup 1.0000x reference)
.LBB0_109:
	v_readlane_b32 s0, v254, 5
	v_readlane_b32 s1, v254, 6
	s_cmp_lt_i32 s0, 3
	s_cselect_b64 s[0:1], -1, 0
	s_add_u32 s6, s26, 0x20000
	s_addc_u32 s7, s27, 0
	s_add_u32 s68, s26, 0x2600000
	s_addc_u32 s69, s27, 0
	v_writelane_b32 v254, s6, 11
	s_waitcnt lgkmcnt(0)
	s_add_u32 s44, s26, 0x3200000
	v_writelane_b32 v254, s7, 12
	s_addc_u32 s6, s27, 0
	s_add_u32 s40, s26, 0x3a00000
	s_addc_u32 s41, s27, 0
	s_add_u32 s28, s26, 0x7d00000
	s_addc_u32 s55, s27, 0
	v_writelane_b32 v254, s6, 13
	s_mov_b32 s45, s6
	s_add_u32 s6, s26, 0x9d00000
	s_addc_u32 s7, s27, 0
	s_add_u32 s58, s26, 0xbd00000
	v_writelane_b32 v254, s6, 14
	s_addc_u32 s59, s27, 0
	s_mov_b32 s54, s28
	v_writelane_b32 v254, s7, 15
	s_add_u32 s6, s26, 0xdd00000
	s_addc_u32 s7, s27, 0
	s_add_u32 s14, s26, 0xed00000
	s_addc_u32 s15, s27, 0
	s_add_u32 s38, s26, 0x10d00000
	s_addc_u32 s39, s27, 0
	s_and_b64 s[80:81], s[0:1], s[4:5]
	v_writelane_b32 v254, s6, 16
	s_andn2_b64 vcc, exec, s[80:81]
	s_nop 0
	v_writelane_b32 v254, s7, 17
	s_cbranch_vccnz .LBB0_377
	v_readlane_b32 s4, v254, 2
	s_cmpk_lt_i32 s4, 0x480
	s_cselect_b64 s[0:1], -1, 0
	s_cmpk_gt_i32 s4, 0x47f
	v_readfirstlane_b32 s4, v0
	s_cbranch_scc1 .LBB0_112
	v_readlane_b32 s7, v254, 2
	s_ashr_i32 s5, s7, 31
	s_lshr_b32 s5, s5, 29
	s_add_i32 s5, s7, s5
	s_ashr_i32 s6, s5, 3
	s_and_b32 s5, s5, -8
	s_sub_i32 s5, s7, s5
	s_cmp_lt_i32 s5, 0
	s_movk_i32 s7, 0x91
	s_cselect_b32 s7, s7, 0x90
	s_mul_i32 s5, s5, s7
	s_add_i32 s5, s5, s6
	s_mul_hi_i32 s6, s5, 0x38e38e39
	s_lshr_b32 s7, s6, 31
	s_ashr_i32 s6, s6, 6
	s_add_i32 s6, s6, s7
	s_lshl_b32 s7, s6, 3
	s_mulk_i32 s6, 0x120
	s_sub_i32 s5, s5, s6
	s_sext_i32_i16 s6, s5
	s_bfe_u32 s6, s6, 0x3001c
	s_add_i32 s6, s5, s6
	s_sext_i32_i16 s8, s6
	s_and_b32 s6, s6, 0xfff8
	s_sub_i32 s5, s5, s6
	s_sext_i32_i16 s5, s5
	s_add_i32 s89, s7, s5
	s_ashr_i32 s42, s8, 3
	s_cmp_gt_u32 s42, 17
	s_cselect_b32 s5, 1, 0
	s_mul_i32 s6, s5, 18
	s_sub_i32 s6, s42, s6
	s_mov_b32 s7, 14
	s_mov_b32 s8, 4
	s_cmp_lt_u32 s6, 14
	s_cselect_b32 s7, 10, s7
	s_cmp_lt_u32 s6, 10
	s_cselect_b32 s7, 8, s7
	s_cselect_b32 s8, 2, s8
	s_cmp_lt_u32 s6, 8
	s_cselect_b32 s7, 4, s7
	s_cselect_b32 s8, 4, s8
	s_cmp_lt_u32 s6, 4
	s_cselect_b32 s7, 0, s7
	s_mul_i32 s8, s8, s5
	s_add_i32 s42, s6, s7
	s_add_i32 s42, s42, s8

.LBB0_118:
	s_add_i32 s49, s49, 1
	v_readlane_b32 s3, v254, 28
	s_mul_i32 s3, s49, s3
	s_mul_hi_u32 s4, s49, s33
	s_add_i32 s4, s4, s3
	s_mul_i32 s3, s49, s33
	v_readlane_b32 s5, v254, 2
	s_add_u32 s8, s3, s5
	v_readlane_b32 s3, v254, 29
	s_addc_u32 s9, s4, s3
	v_cmp_gt_i64_e32 vcc, s[8:9], v[136:137]
	v_cmp_lt_i64_e64 s[4:5], s[8:9], v[134:135]
	s_cbranch_vccnz .LBB0_120
	s_ashr_i32 s3, s8, 31
	s_lshr_b32 s3, s3, 29
	s_add_i32 s3, s8, s3
	s_ashr_i32 s9, s3, 3
	s_and_b32 s3, s3, -8
	s_sub_i32 s3, s8, s3
	s_cmp_lt_i32 s3, 0
	s_movk_i32 s8, 0x91
	s_cselect_b32 s8, s8, 0x90
	s_mul_i32 s3, s3, s8
	s_add_i32 s3, s3, s9
	s_mul_hi_i32 s8, s3, 0x38e38e39
	s_lshr_b32 s9, s8, 31
	s_ashr_i32 s8, s8, 6
	s_add_i32 s8, s8, s9
	s_lshl_b32 s9, s8, 3
	s_sub_i32 s12, 32, s9
	s_min_i32 s12, s12, 8
	s_abs_i32 s13, s12
	v_cvt_f32_u32_e32 v3, s13
	s_sub_i32 s46, 0, s13
	s_mulk_i32 s8, 0x120
	s_sub_i32 s3, s3, s8
	v_rcp_iflag_f32_e32 v3, v3
	s_abs_i32 s8, s3
	s_xor_b32 s43, s3, s12
	s_ashr_i32 s43, s43, 31
	v_mul_f32_e32 v3, 0x4f7ffffe, v3
	v_cvt_u32_f32_e32 v3, v3
	s_nop 0
	v_readfirstlane_b32 s47, v3
	s_mul_i32 s46, s46, s47
	s_mul_hi_u32 s46, s47, s46
	s_add_i32 s47, s47, s46
	s_mul_hi_u32 s46, s8, s47
	s_mul_i32 s47, s46, s13
	s_sub_i32 s8, s8, s47
	s_add_i32 s75, s46, 1
	s_sub_i32 s47, s8, s13
	s_cmp_ge_u32 s8, s13
	s_cselect_b32 s46, s75, s46
	s_cselect_b32 s8, s47, s8
	s_add_i32 s47, s46, 1
	s_cmp_ge_u32 s8, s13
	s_cselect_b32 s8, s47, s46
	s_xor_b32 s8, s8, s43
	s_sub_i32 s46, s8, s43
	s_mul_i32 s8, s46, s12
	s_sub_i32 s3, s3, s8
	s_add_i32 s43, s9, s3
	s_cmp_gt_u32 s46, 17
	s_cselect_b32 s3, 1, 0
	s_mul_i32 s8, s3, 18
	s_sub_i32 s8, s46, s8
	s_mov_b32 s9, 14
	s_mov_b32 s12, 4
	s_cmp_lt_u32 s8, 14
	s_cselect_b32 s9, 10, s9
	s_cmp_lt_u32 s8, 10
	s_cselect_b32 s9, 8, s9
	s_cselect_b32 s12, 2, s12
	s_cmp_lt_u32 s8, 8
	s_cselect_b32 s9, 4, s9
	s_cselect_b32 s12, 4, s12
	s_cmp_lt_u32 s8, 4
	s_cselect_b32 s9, 0, s9
	s_mul_i32 s12, s12, s3
	s_add_i32 s46, s8, s9
	s_add_i32 s46, s46, s12
